# GEMM K-loops: mid-block s_setprio 0/1 pair removed (block keeps priority 1 from its late raise to the end)
# speedup vs baseline: 1.0210x; 1.0210x over previous
; #define PG8_STAGE(bufoff, gbase, voff) do { _Pragma("unroll") for (int _i = 0; _i < 2; ++_i) \
;         __builtin_amdgcn_global_load_lds((const unsigned*)((const char*)(gbase) + (voff)[_i]), (PG8_LAS unsigned*)(lds + (bufoff) + ldsw + _i * 8192), 16, 0, 0); } while (0)
; #define PG8_LDA(dst, b, h) do { _Pragma("unroll") for (int m = 0; m < 4; ++m) _Pragma("unroll") for (int k = 0; k < 2; ++k) dst[m][k] = *(const PG8_LAS bf16x8*)(lds + PG8_SA(b, h) + aoff + m * 2048 + k * 1024); } while (0)
; #define PG8_LDB(dst, b, h) do { _Pragma("unroll") for (int n = 0; n < 2; ++n) _Pragma("unroll") for (int k = 0; k < 2; ++k) dst[n][k] = *(const PG8_LAS bf16x8*)(lds + PG8_SB(b, h) + boff + n * 2048 + k * 1024); } while (0)
; #define PG8_MMA(ai, bj, At, Bt) do { __builtin_amdgcn_s_setprio(1); _Pragma("unroll") for (int m = 0; m < 4; ++m) _Pragma("unroll") for (int n = 0; n < 2; ++n) _Pragma("unroll") for (int k = 0; k < 2; ++k) \
;         acc[ai][bj][m][n] = __builtin_amdgcn_mfma_f32_16x16x32_bf16(Bt[n][k], At[m][k], acc[ai][bj][m][n], 0, 0, 0); __builtin_amdgcn_s_setprio(0); } while (0)
; #define PG8_WAIT_V(n) asm volatile("s_waitcnt vmcnt(" #n ")" ::: "memory")
; #define PG8_WAIT_L(n) asm volatile("s_waitcnt lgkmcnt(" #n ")" ::: "memory")
; #define PG8_BAR __builtin_amdgcn_s_barrier()
; #define PG8_SCHED __builtin_amdgcn_sched_barrier(0)
; template <class Epi, class Sched, bool ALIGN_EPI = false, bool SP2 = false>
; __device__ __forceinline__ void gemm_phase(PG8_LAS unsigned char* lds, const Gemm g, const Sched& S, const Epi& E) {
;     ...
;             PG8_LDB(B0, 0, 0); PG8_LDB(B1, 0, 1); PG8_SCHED; PG8_LDA(At, 0, 0); PG8_STAGE(PG8_SA(1, 1), a1 + hstep, voffA);
;             PG8_WAIT_V(8); PG8_WAIT_L(0); PG8_BAR; PG8_MMA(0, 0, At, B0); PG8_MMA(0, 1, At, B1); PG8_BAR; PG8_SCHED;
;             PG8_LDA(At, 0, 1); PG8_STAGE(PG8_SB(0, 0), b2, voffB); PG8_STAGE(PG8_SB(0, 1), b2 + hstep, voffB); PG8_STAGE(PG8_SA(0, 0), a2, voffA);
;             PG8_WAIT_V(8); PG8_WAIT_L(0); PG8_BAR; PG8_MMA(1, 0, At, B0); PG8_MMA(1, 1, At, B1); PG8_BAR; PG8_SCHED;
.LBB0_165:
	s_add_i32 s18, 0, 0x10000
	v_add_u32_e32 v0, s18, v194
	s_add_i32 s19, 0, 0x14000
	ds_read_b128 v[136:139], v0
	ds_read_b128 v[140:143], v0 offset:1024
	ds_read_b128 v[144:147], v0 offset:2048
	ds_read_b128 v[148:151], v0 offset:3072
	v_add_u32_e32 v0, s19, v194
	ds_read_b128 v[152:155], v0
	ds_read_b128 v[186:189], v0 offset:1024
	ds_read_b128 v[190:193], v0 offset:2048
	ds_read_b128 v[198:201], v0 offset:3072
	v_lshl_add_u64 v[2:3], s[8:9], 0, v[182:183]
	s_add_i32 m0, s45, 0xc000
	ds_read_b128 v[210:213], v196
	ds_read_b128 v[214:217], v196 offset:1024
	ds_read_b128 v[218:221], v196 offset:2048
	ds_read_b128 v[222:225], v196 offset:3072
	ds_read_b128 v[226:229], v196 offset:4096
	ds_read_b128 v[230:233], v196 offset:5120
	ds_read_b128 v[234:237], v196 offset:6144
	ds_read_b128 v[238:241], v196 offset:7168
	global_load_lds_dwordx4 v[2:3], off
	v_lshl_add_u64 v[2:3], s[8:9], 0, v[184:185]
	s_add_i32 m0, s45, 0xe000
	s_nop 0
	global_load_lds_dwordx4 v[2:3], off
	s_waitcnt vmcnt(8)
	s_waitcnt lgkmcnt(0)
	s_barrier
	s_waitcnt lgkmcnt(0)
	v_mfma_f32_16x16x32_bf16 v[132:135], v[136:139], v[210:213], v[132:135]
	v_mfma_f32_16x16x32_bf16 v[128:131], v[144:147], v[210:213], v[128:131]
	v_mfma_f32_16x16x32_bf16 v[124:127], v[136:139], v[218:221], v[124:127]
	v_mfma_f32_16x16x32_bf16 v[120:123], v[144:147], v[218:221], v[120:123]
	s_setprio 1
	v_mfma_f32_16x16x32_bf16 v[116:119], v[136:139], v[226:229], v[116:119]
	v_mfma_f32_16x16x32_bf16 v[112:115], v[144:147], v[226:229], v[112:115]
	v_mfma_f32_16x16x32_bf16 v[108:111], v[136:139], v[234:237], v[108:111]
	v_mfma_f32_16x16x32_bf16 v[104:107], v[144:147], v[234:237], v[104:107]
	v_mfma_f32_16x16x32_bf16 v[132:135], v[140:143], v[214:217], v[132:135]
	v_mfma_f32_16x16x32_bf16 v[128:131], v[148:151], v[214:217], v[128:131]
	v_mfma_f32_16x16x32_bf16 v[124:127], v[140:143], v[222:225], v[124:127]
	v_mfma_f32_16x16x32_bf16 v[120:123], v[148:151], v[222:225], v[120:123]
	v_mfma_f32_16x16x32_bf16 v[116:119], v[140:143], v[230:233], v[116:119]
	v_mfma_f32_16x16x32_bf16 v[112:115], v[148:151], v[230:233], v[112:115]
	v_mfma_f32_16x16x32_bf16 v[108:111], v[140:143], v[238:241], v[108:111]
	v_mfma_f32_16x16x32_bf16 v[104:107], v[148:151], v[238:241], v[104:107]
	v_mfma_f32_16x16x32_bf16 v[84:87], v[152:155], v[210:213], v[84:87]
	v_mfma_f32_16x16x32_bf16 v[76:79], v[190:193], v[210:213], v[76:79]
	v_mfma_f32_16x16x32_bf16 v[68:71], v[152:155], v[218:221], v[68:71]
	v_mfma_f32_16x16x32_bf16 v[64:67], v[190:193], v[218:221], v[64:67]
	v_mfma_f32_16x16x32_bf16 v[52:55], v[152:155], v[226:229], v[52:55]
	v_mfma_f32_16x16x32_bf16 v[48:51], v[190:193], v[226:229], v[48:51]
	v_mfma_f32_16x16x32_bf16 v[44:47], v[152:155], v[234:237], v[44:47]
	v_mfma_f32_16x16x32_bf16 v[40:43], v[190:193], v[234:237], v[40:43]
	v_mfma_f32_16x16x32_bf16 v[84:87], v[186:189], v[214:217], v[84:87]
	v_mfma_f32_16x16x32_bf16 v[76:79], v[198:201], v[214:217], v[76:79]
	v_mfma_f32_16x16x32_bf16 v[68:71], v[186:189], v[222:225], v[68:71]
	v_mfma_f32_16x16x32_bf16 v[64:67], v[198:201], v[222:225], v[64:67]
	s_barrier
	v_mfma_f32_16x16x32_bf16 v[52:55], v[186:189], v[230:233], v[52:55]
	v_mfma_f32_16x16x32_bf16 v[48:51], v[198:201], v[230:233], v[48:51]
	v_mfma_f32_16x16x32_bf16 v[44:47], v[186:189], v[238:241], v[44:47]
	v_mfma_f32_16x16x32_bf16 v[40:43], v[198:201], v[238:241], v[40:43]
	s_setprio 0
	s_add_i32 s16, s18, s44
	v_lshl_add_u64 v[2:3], s[40:41], 0, v[162:163]
	s_mov_b32 m0, s16
	ds_read_b128 v[210:213], v196 offset:16384
	ds_read_b128 v[214:217], v196 offset:17408
	ds_read_b128 v[218:221], v196 offset:18432
	ds_read_b128 v[222:225], v196 offset:19456
	ds_read_b128 v[226:229], v196 offset:20480
	ds_read_b128 v[230:233], v196 offset:21504
	ds_read_b128 v[234:237], v196 offset:22528
	ds_read_b128 v[238:241], v196 offset:23552
	global_load_lds_dwordx4 v[2:3], off
	s_add_i32 m0, s16, 0x2000
	s_add_u32 s16, s40, 0x40000
	v_lshl_add_u64 v[156:157], s[40:41], 0, v[158:159]
	s_addc_u32 s17, s41, 0
	s_add_i32 s18, s19, s44
	global_load_lds_dwordx4 v[156:157], off
	v_lshl_add_u64 v[242:243], s[16:17], 0, v[162:163]
	s_mov_b32 m0, s18
	v_lshl_add_u64 v[244:245], s[42:43], 0, v[160:161]
	global_load_lds_dwordx4 v[242:243], off
	v_lshl_add_u64 v[242:243], s[16:17], 0, v[158:159]
	s_add_i32 m0, s18, 0x2000
	s_nop 0
	global_load_lds_dwordx4 v[242:243], off
	v_lshl_add_u64 v[242:243], s[42:43], 0, v[178:179]
	s_waitcnt vmcnt(6)
	s_waitcnt lgkmcnt(0)
	s_barrier
	s_waitcnt lgkmcnt(0)
	v_mfma_f32_16x16x32_bf16 v[100:103], v[136:139], v[210:213], v[100:103]
	v_mfma_f32_16x16x32_bf16 v[96:99], v[144:147], v[210:213], v[96:99]
	v_mfma_f32_16x16x32_bf16 v[92:95], v[136:139], v[218:221], v[92:95]
	s_mov_b32 m0, s45
	v_mfma_f32_16x16x32_bf16 v[88:91], v[144:147], v[218:221], v[88:91]
	s_setprio 1
	global_load_lds_dwordx4 v[242:243], off
	v_mfma_f32_16x16x32_bf16 v[80:83], v[136:139], v[226:229], v[80:83]
	v_mfma_f32_16x16x32_bf16 v[72:75], v[144:147], v[226:229], v[72:75]
	v_mfma_f32_16x16x32_bf16 v[60:63], v[136:139], v[234:237], v[60:63]
	v_mfma_f32_16x16x32_bf16 v[56:59], v[144:147], v[234:237], v[56:59]
	v_mfma_f32_16x16x32_bf16 v[100:103], v[140:143], v[214:217], v[100:103]
	v_mfma_f32_16x16x32_bf16 v[96:99], v[148:151], v[214:217], v[96:99]
	v_mfma_f32_16x16x32_bf16 v[92:95], v[140:143], v[222:225], v[92:95]
	s_mov_b32 m0, s46
	v_mfma_f32_16x16x32_bf16 v[88:91], v[148:151], v[222:225], v[88:91]
	global_load_lds_dwordx4 v[244:245], off
	v_mfma_f32_16x16x32_bf16 v[80:83], v[140:143], v[230:233], v[80:83]
	v_mfma_f32_16x16x32_bf16 v[72:75], v[148:151], v[230:233], v[72:75]
	v_mfma_f32_16x16x32_bf16 v[60:63], v[140:143], v[238:241], v[60:63]
	v_mfma_f32_16x16x32_bf16 v[56:59], v[148:151], v[238:241], v[56:59]
	v_mfma_f32_16x16x32_bf16 v[36:39], v[152:155], v[210:213], v[36:39]
	v_mfma_f32_16x16x32_bf16 v[32:35], v[190:193], v[210:213], v[32:35]
	v_mfma_f32_16x16x32_bf16 v[28:31], v[152:155], v[218:221], v[28:31]
	v_mfma_f32_16x16x32_bf16 v[24:27], v[190:193], v[218:221], v[24:27]
	v_mfma_f32_16x16x32_bf16 v[20:23], v[152:155], v[226:229], v[20:23]
	v_mfma_f32_16x16x32_bf16 v[16:19], v[190:193], v[226:229], v[16:19]
	v_mfma_f32_16x16x32_bf16 v[12:15], v[152:155], v[234:237], v[12:15]
	v_mfma_f32_16x16x32_bf16 v[8:11], v[190:193], v[234:237], v[8:11]
	v_mfma_f32_16x16x32_bf16 v[36:39], v[186:189], v[214:217], v[36:39]
	v_mfma_f32_16x16x32_bf16 v[32:35], v[198:201], v[214:217], v[32:35]
	v_mfma_f32_16x16x32_bf16 v[28:31], v[186:189], v[222:225], v[28:31]
	v_mfma_f32_16x16x32_bf16 v[24:27], v[198:201], v[222:225], v[24:27]
	s_barrier
; #define PG8_STAGE(bufoff, gbase, voff) do { _Pragma("unroll") for (int _i = 0; _i < 2; ++_i) \
;         __builtin_amdgcn_global_load_lds((const unsigned*)((const char*)(gbase) + (voff)[_i]), (PG8_LAS unsigned*)(lds + (bufoff) + ldsw + _i * 8192), 16, 0, 0); } while (0)
; #define PG8_LDA(dst, b, h) do { _Pragma("unroll") for (int m = 0; m < 4; ++m) _Pragma("unroll") for (int k = 0; k < 2; ++k) dst[m][k] = *(const PG8_LAS bf16x8*)(lds + PG8_SA(b, h) + aoff + m * 2048 + k * 1024); } while (0)
; #define PG8_LDB(dst, b, h) do { _Pragma("unroll") for (int n = 0; n < 2; ++n) _Pragma("unroll") for (int k = 0; k < 2; ++k) dst[n][k] = *(const PG8_LAS bf16x8*)(lds + PG8_SB(b, h) + boff + n * 2048 + k * 1024); } while (0)
; #define PG8_MMA(ai, bj, At, Bt) do { __builtin_amdgcn_s_setprio(1); _Pragma("unroll") for (int m = 0; m < 4; ++m) _Pragma("unroll") for (int n = 0; n < 2; ++n) _Pragma("unroll") for (int k = 0; k < 2; ++k) \
;         acc[ai][bj][m][n] = __builtin_amdgcn_mfma_f32_16x16x32_bf16(Bt[n][k], At[m][k], acc[ai][bj][m][n], 0, 0, 0); __builtin_amdgcn_s_setprio(0); } while (0)
; #define PG8_WAIT_V(n) asm volatile("s_waitcnt vmcnt(" #n ")" ::: "memory")
; #define PG8_WAIT_L(n) asm volatile("s_waitcnt lgkmcnt(" #n ")" ::: "memory")
; #define PG8_BAR __builtin_amdgcn_s_barrier()
; #define PG8_SCHED __builtin_amdgcn_sched_barrier(0)
; template <class Epi, class Sched, bool ALIGN_EPI = false, bool SP2 = false>
; __device__ __forceinline__ void gemm_phase(PG8_LAS unsigned char* lds, const Gemm g, const Sched& S, const Epi& E) {
;     ...
;             PG8_WAIT_V(8); PG8_WAIT_L(0); PG8_BAR; PG8_MMA(1, 0, At, B0); PG8_MMA(1, 1, At, B1); PG8_BAR; PG8_SCHED;
;             PG8_LDB(B0, 1, 0); PG8_LDB(B1, 1, 1); PG8_SCHED; PG8_LDA(At, 1, 0); PG8_STAGE(PG8_SA(0, 1), a2 + hstep, voffA);
;             PG8_WAIT_V(8); PG8_WAIT_L(0); PG8_BAR; PG8_MMA(0, 0, At, B0); PG8_MMA(0, 1, At, B1); PG8_BAR; PG8_SCHED;
	v_mfma_f32_16x16x32_bf16 v[20:23], v[186:189], v[230:233], v[20:23]
	v_mfma_f32_16x16x32_bf16 v[16:19], v[198:201], v[230:233], v[16:19]
	v_mfma_f32_16x16x32_bf16 v[12:15], v[186:189], v[238:241], v[12:15]
	v_mfma_f32_16x16x32_bf16 v[8:11], v[198:201], v[238:241], v[8:11]
	s_setprio 0
	s_add_i32 s18, 0, 0x18000
	v_add_u32_e32 v0, s18, v194
	ds_read_b128 v[136:139], v0
	ds_read_b128 v[140:143], v0 offset:1024
	ds_read_b128 v[144:147], v0 offset:2048
	ds_read_b128 v[148:151], v0 offset:3072
	v_add_u32_e32 v0, s33, v194
	ds_read_b128 v[152:155], v0
	ds_read_b128 v[186:189], v0 offset:1024
	ds_read_b128 v[190:193], v0 offset:2048
	ds_read_b128 v[198:201], v0 offset:3072
	s_add_u32 s16, s42, 0x40000
	s_addc_u32 s17, s43, 0
	s_mov_b32 m0, s47
	v_lshl_add_u64 v[246:247], s[16:17], 0, v[178:179]
	ds_read_b128 v[210:213], v196 offset:32768
	ds_read_b128 v[214:217], v196 offset:33792
	ds_read_b128 v[218:221], v196 offset:34816
	ds_read_b128 v[222:225], v196 offset:35840
	ds_read_b128 v[226:229], v196 offset:36864
	ds_read_b128 v[230:233], v196 offset:37888
	ds_read_b128 v[234:237], v196 offset:38912
	ds_read_b128 v[238:241], v196 offset:39936
	global_load_lds_dwordx4 v[246:247], off
	v_lshl_add_u64 v[246:247], s[16:17], 0, v[160:161]
	s_mov_b32 m0, s48
	s_nop 0
	global_load_lds_dwordx4 v[246:247], off
	s_waitcnt vmcnt(8)
	s_waitcnt lgkmcnt(0)
	s_barrier
	s_waitcnt lgkmcnt(0)
	v_mfma_f32_16x16x32_bf16 v[132:135], v[136:139], v[210:213], v[132:135]
	v_mfma_f32_16x16x32_bf16 v[128:131], v[144:147], v[210:213], v[128:131]
	v_mfma_f32_16x16x32_bf16 v[124:127], v[136:139], v[218:221], v[124:127]
	v_mfma_f32_16x16x32_bf16 v[120:123], v[144:147], v[218:221], v[120:123]
	s_setprio 1
	v_mfma_f32_16x16x32_bf16 v[116:119], v[136:139], v[226:229], v[116:119]
	v_mfma_f32_16x16x32_bf16 v[112:115], v[144:147], v[226:229], v[112:115]
	v_mfma_f32_16x16x32_bf16 v[108:111], v[136:139], v[234:237], v[108:111]
	v_mfma_f32_16x16x32_bf16 v[104:107], v[144:147], v[234:237], v[104:107]
	v_mfma_f32_16x16x32_bf16 v[132:135], v[140:143], v[214:217], v[132:135]
	v_mfma_f32_16x16x32_bf16 v[128:131], v[148:151], v[214:217], v[128:131]
	v_mfma_f32_16x16x32_bf16 v[124:127], v[140:143], v[222:225], v[124:127]
	v_mfma_f32_16x16x32_bf16 v[120:123], v[148:151], v[222:225], v[120:123]
	v_mfma_f32_16x16x32_bf16 v[116:119], v[140:143], v[230:233], v[116:119]
	v_mfma_f32_16x16x32_bf16 v[112:115], v[148:151], v[230:233], v[112:115]
	v_mfma_f32_16x16x32_bf16 v[108:111], v[140:143], v[238:241], v[108:111]
	v_mfma_f32_16x16x32_bf16 v[104:107], v[148:151], v[238:241], v[104:107]
	v_mfma_f32_16x16x32_bf16 v[84:87], v[152:155], v[210:213], v[84:87]
	v_mfma_f32_16x16x32_bf16 v[76:79], v[190:193], v[210:213], v[76:79]
	v_mfma_f32_16x16x32_bf16 v[68:71], v[152:155], v[218:221], v[68:71]
	v_mfma_f32_16x16x32_bf16 v[64:67], v[190:193], v[218:221], v[64:67]
	v_mfma_f32_16x16x32_bf16 v[52:55], v[152:155], v[226:229], v[52:55]
	v_mfma_f32_16x16x32_bf16 v[48:51], v[190:193], v[226:229], v[48:51]
	v_mfma_f32_16x16x32_bf16 v[44:47], v[152:155], v[234:237], v[44:47]
	v_mfma_f32_16x16x32_bf16 v[40:43], v[190:193], v[234:237], v[40:43]
	v_mfma_f32_16x16x32_bf16 v[84:87], v[186:189], v[214:217], v[84:87]
	v_mfma_f32_16x16x32_bf16 v[76:79], v[198:201], v[214:217], v[76:79]
	v_mfma_f32_16x16x32_bf16 v[68:71], v[186:189], v[222:225], v[68:71]
	v_mfma_f32_16x16x32_bf16 v[64:67], v[198:201], v[222:225], v[64:67]
	s_barrier
; #define PG8_STAGE(bufoff, gbase, voff) do { _Pragma("unroll") for (int _i = 0; _i < 2; ++_i) \
;         __builtin_amdgcn_global_load_lds((const unsigned*)((const char*)(gbase) + (voff)[_i]), (PG8_LAS unsigned*)(lds + (bufoff) + ldsw + _i * 8192), 16, 0, 0); } while (0)
; #define PG8_LDA(dst, b, h) do { _Pragma("unroll") for (int m = 0; m < 4; ++m) _Pragma("unroll") for (int k = 0; k < 2; ++k) dst[m][k] = *(const PG8_LAS bf16x8*)(lds + PG8_SA(b, h) + aoff + m * 2048 + k * 1024); } while (0)
; #define PG8_MMA(ai, bj, At, Bt) do { __builtin_amdgcn_s_setprio(1); _Pragma("unroll") for (int m = 0; m < 4; ++m) _Pragma("unroll") for (int n = 0; n < 2; ++n) _Pragma("unroll") for (int k = 0; k < 2; ++k) \
;         acc[ai][bj][m][n] = __builtin_amdgcn_mfma_f32_16x16x32_bf16(Bt[n][k], At[m][k], acc[ai][bj][m][n], 0, 0, 0); __builtin_amdgcn_s_setprio(0); } while (0)
; #define PG8_WAIT_V(n) asm volatile("s_waitcnt vmcnt(" #n ")" ::: "memory")
; #define PG8_WAIT_L(n) asm volatile("s_waitcnt lgkmcnt(" #n ")" ::: "memory")
; #define PG8_BAR __builtin_amdgcn_s_barrier()
; #define PG8_SCHED __builtin_amdgcn_sched_barrier(0)
; template <class Epi, class Sched, bool ALIGN_EPI = false, bool SP2 = false>
; __device__ __forceinline__ void gemm_phase(PG8_LAS unsigned char* lds, const Gemm g, const Sched& S, const Epi& E) {
;     ...
;         for (int t = 0; t < nt; t += 2) {
;             const bool last = (t == nt - 2);
;             const char* a1 = cA + (size_t)(t + 1) * kstep;
;             const char* a2 = last ? nA : cA + (size_t)(t + 2) * kstep; const char* b2 = last ? nB : cB + (size_t)(t + 2) * kstep;
;             const char* a3 = a2 + kstep; const char* b3 = b2 + kstep;
;     ...
;             PG8_WAIT_V(8); PG8_WAIT_L(0); PG8_BAR; PG8_MMA(0, 0, At, B0); PG8_MMA(0, 1, At, B1); PG8_BAR; PG8_SCHED;
;             PG8_LDA(At, 1, 1); PG8_STAGE(PG8_SB(1, 0), b3, voffB); PG8_STAGE(PG8_SB(1, 1), b3 + hstep, voffB); PG8_STAGE(PG8_SA(1, 0), a3, voffA);
;             PG8_WAIT_V(8); PG8_WAIT_L(0); PG8_BAR; PG8_MMA(1, 0, At, B0); PG8_MMA(1, 1, At, B1); PG8_BAR; PG8_SCHED;
	v_mfma_f32_16x16x32_bf16 v[52:55], v[186:189], v[230:233], v[52:55]
	v_mfma_f32_16x16x32_bf16 v[48:51], v[198:201], v[230:233], v[48:51]
	v_mfma_f32_16x16x32_bf16 v[44:47], v[186:189], v[238:241], v[44:47]
	v_mfma_f32_16x16x32_bf16 v[40:43], v[198:201], v[238:241], v[40:43]
	s_setprio 0
	s_add_i32 s16, s18, s44
	v_lshl_add_u64 v[2:3], v[2:3], 0, s[20:21]
	s_mov_b32 m0, s16
	ds_read_b128 v[210:213], v196 offset:49152
	ds_read_b128 v[214:217], v196 offset:50176
	ds_read_b128 v[218:221], v196 offset:51200
	ds_read_b128 v[222:225], v196 offset:52224
	ds_read_b128 v[226:229], v196 offset:53248
	ds_read_b128 v[230:233], v196 offset:54272
	ds_read_b128 v[234:237], v196 offset:55296
	ds_read_b128 v[238:241], v196 offset:56320
	global_load_lds_dwordx4 v[2:3], off
	s_add_i32 m0, s16, 0x2000
	s_add_u32 s16, s40, 0x40080
	v_lshl_add_u64 v[2:3], v[156:157], 0, s[20:21]
	s_addc_u32 s17, s41, 0
	s_add_i32 s18, s33, s44
	global_load_lds_dwordx4 v[2:3], off
	v_lshl_add_u64 v[2:3], s[16:17], 0, v[162:163]
	s_mov_b32 m0, s18
	s_nop 0
	global_load_lds_dwordx4 v[2:3], off
	v_lshl_add_u64 v[2:3], s[16:17], 0, v[158:159]
	s_add_i32 m0, s18, 0x2000
	s_nop 0
	global_load_lds_dwordx4 v[2:3], off
	v_lshl_add_u64 v[2:3], v[242:243], 0, s[20:21]
	v_lshl_add_u64 v[244:245], v[244:245], 0, s[20:21]
	s_waitcnt vmcnt(6)
	s_waitcnt lgkmcnt(0)
	s_barrier
	s_waitcnt lgkmcnt(0)
	v_mfma_f32_16x16x32_bf16 v[100:103], v[136:139], v[210:213], v[100:103]
	v_mfma_f32_16x16x32_bf16 v[96:99], v[144:147], v[210:213], v[96:99]
	v_mfma_f32_16x16x32_bf16 v[92:95], v[136:139], v[218:221], v[92:95]
	s_mov_b32 m0, s49
	v_mfma_f32_16x16x32_bf16 v[88:91], v[144:147], v[218:221], v[88:91]
	s_setprio 1
	global_load_lds_dwordx4 v[2:3], off
	v_mfma_f32_16x16x32_bf16 v[80:83], v[136:139], v[226:229], v[80:83]
	v_mfma_f32_16x16x32_bf16 v[72:75], v[144:147], v[226:229], v[72:75]
	v_mfma_f32_16x16x32_bf16 v[60:63], v[136:139], v[234:237], v[60:63]
	s_add_i32 s55, s55, 2
	v_mfma_f32_16x16x32_bf16 v[56:59], v[144:147], v[234:237], v[56:59]
	s_add_u32 s8, s8, 0x100
	s_addc_u32 s9, s9, 0
	v_mfma_f32_16x16x32_bf16 v[100:103], v[140:143], v[214:217], v[100:103]
	s_add_u32 s53, s53, 0x100
	s_addc_u32 s54, s54, 0
	v_mfma_f32_16x16x32_bf16 v[96:99], v[148:151], v[214:217], v[96:99]
	s_add_u32 s16, s8, 0xfffc0080
	s_addc_u32 s17, s9, -1
	v_mfma_f32_16x16x32_bf16 v[92:95], v[140:143], v[222:225], v[92:95]
	s_cmp_eq_u32 s55, 12
	s_cselect_b32 s43, s14, s17
	s_cselect_b32 s42, s15, s16
	s_mov_b32 m0, s50
	v_mfma_f32_16x16x32_bf16 v[88:91], v[148:151], v[222:225], v[88:91]
	s_cselect_b32 s41, s13, s54
	s_cselect_b32 s40, s25, s53
	global_load_lds_dwordx4 v[244:245], off
	v_mfma_f32_16x16x32_bf16 v[80:83], v[140:143], v[230:233], v[80:83]
	v_mfma_f32_16x16x32_bf16 v[72:75], v[148:151], v[230:233], v[72:75]
	v_mfma_f32_16x16x32_bf16 v[60:63], v[140:143], v[238:241], v[60:63]
	v_mfma_f32_16x16x32_bf16 v[56:59], v[148:151], v[238:241], v[56:59]
	v_mfma_f32_16x16x32_bf16 v[36:39], v[152:155], v[210:213], v[36:39]
	v_mfma_f32_16x16x32_bf16 v[32:35], v[190:193], v[210:213], v[32:35]
	v_mfma_f32_16x16x32_bf16 v[28:31], v[152:155], v[218:221], v[28:31]
	v_mfma_f32_16x16x32_bf16 v[24:27], v[190:193], v[218:221], v[24:27]
	v_mfma_f32_16x16x32_bf16 v[20:23], v[152:155], v[226:229], v[20:23]
	v_mfma_f32_16x16x32_bf16 v[16:19], v[190:193], v[226:229], v[16:19]
	v_mfma_f32_16x16x32_bf16 v[12:15], v[152:155], v[234:237], v[12:15]
	v_mfma_f32_16x16x32_bf16 v[8:11], v[190:193], v[234:237], v[8:11]
	v_mfma_f32_16x16x32_bf16 v[36:39], v[186:189], v[214:217], v[36:39]
	v_mfma_f32_16x16x32_bf16 v[32:35], v[198:201], v[214:217], v[32:35]
	v_mfma_f32_16x16x32_bf16 v[28:31], v[186:189], v[222:225], v[28:31]
	v_mfma_f32_16x16x32_bf16 v[24:27], v[198:201], v[222:225], v[24:27]
	s_barrier
	v_mfma_f32_16x16x32_bf16 v[20:23], v[186:189], v[230:233], v[20:23]
	v_mfma_f32_16x16x32_bf16 v[16:19], v[198:201], v[230:233], v[16:19]
	v_mfma_f32_16x16x32_bf16 v[12:15], v[186:189], v[238:241], v[12:15]
	v_mfma_f32_16x16x32_bf16 v[8:11], v[198:201], v[238:241], v[8:11]
	s_setprio 0
	s_cmp_gt_u32 s55, 13
	s_cbranch_scc0 .LBB0_165
	s_and_b64 vcc, exec, s[10:11]
	s_cbranch_vccz .LBB0_168
	s_barrier
	s_setprio 1

; #define PG8_STAGE(bufoff, gbase, voff) do { _Pragma("unroll") for (int _i = 0; _i < 2; ++_i) \
;         __builtin_amdgcn_global_load_lds((const unsigned*)((const char*)(gbase) + (voff)[_i]), (PG8_LAS unsigned*)(lds + (bufoff) + ldsw + _i * 8192), 16, 0, 0); } while (0)
; #define PG8_LDA(dst, b, h) do { _Pragma("unroll") for (int m = 0; m < 4; ++m) _Pragma("unroll") for (int k = 0; k < 2; ++k) dst[m][k] = *(const PG8_LAS bf16x8*)(lds + PG8_SA(b, h) + aoff + m * 2048 + k * 1024); } while (0)
; #define PG8_LDB(dst, b, h) do { _Pragma("unroll") for (int n = 0; n < 2; ++n) _Pragma("unroll") for (int k = 0; k < 2; ++k) dst[n][k] = *(const PG8_LAS bf16x8*)(lds + PG8_SB(b, h) + boff + n * 2048 + k * 1024); } while (0)
; #define PG8_MMA(ai, bj, At, Bt) do { __builtin_amdgcn_s_setprio(1); _Pragma("unroll") for (int m = 0; m < 4; ++m) _Pragma("unroll") for (int n = 0; n < 2; ++n) _Pragma("unroll") for (int k = 0; k < 2; ++k) \
;         acc[ai][bj][m][n] = __builtin_amdgcn_mfma_f32_16x16x32_bf16(Bt[n][k], At[m][k], acc[ai][bj][m][n], 0, 0, 0); __builtin_amdgcn_s_setprio(0); } while (0)
; #define PG8_WAIT_V(n) asm volatile("s_waitcnt vmcnt(" #n ")" ::: "memory")
; #define PG8_WAIT_L(n) asm volatile("s_waitcnt lgkmcnt(" #n ")" ::: "memory")
; #define PG8_BAR __builtin_amdgcn_s_barrier()
; #define PG8_SCHED __builtin_amdgcn_sched_barrier(0)
; template <class Epi, class Sched, bool ALIGN_EPI = false, bool SP2 = false>
; __device__ __forceinline__ void gemm_phase(PG8_LAS unsigned char* lds, const Gemm g, const Sched& S, const Epi& E) {
;     ...
;             PG8_LDB(B0, 0, 0); PG8_LDB(B1, 0, 1); PG8_SCHED; PG8_LDA(At, 0, 0); PG8_STAGE(PG8_SA(1, 1), a1 + hstep, voffA);
;             PG8_WAIT_V(8); PG8_WAIT_L(0); PG8_BAR; PG8_MMA(0, 0, At, B0); PG8_MMA(0, 1, At, B1); PG8_BAR; PG8_SCHED;
;             PG8_LDA(At, 0, 1); PG8_STAGE(PG8_SB(0, 0), b2, voffB); PG8_STAGE(PG8_SB(0, 1), b2 + hstep, voffB); PG8_STAGE(PG8_SA(0, 0), a2, voffA);
;             PG8_WAIT_V(8); PG8_WAIT_L(0); PG8_BAR; PG8_MMA(1, 0, At, B0); PG8_MMA(1, 1, At, B1); PG8_BAR; PG8_SCHED;
.LBB0_203:
	s_add_i32 s18, 0, 0x10000
	v_add_u32_e32 v137, s18, v200
	s_add_i32 s19, 0, 0x14000
	ds_read_b128 v[144:147], v137
	ds_read_b128 v[148:151], v137 offset:1024
	ds_read_b128 v[152:155], v137 offset:2048
	ds_read_b128 v[156:159], v137 offset:3072
	v_add_u32_e32 v137, s19, v200
	ds_read_b128 v[160:163], v137
	ds_read_b128 v[178:181], v137 offset:1024
	ds_read_b128 v[182:185], v137 offset:2048
	ds_read_b128 v[186:189], v137 offset:3072
	v_lshl_add_u64 v[198:199], s[24:25], 0, v[140:141]
	s_add_i32 m0, s52, 0xc000
	ds_read_b128 v[190:193], v210
	ds_read_b128 v[194:197], v210 offset:1024
	ds_read_b128 v[212:215], v210 offset:2048
	ds_read_b128 v[216:219], v210 offset:3072
	ds_read_b128 v[220:223], v210 offset:4096
	ds_read_b128 v[224:227], v210 offset:5120
	ds_read_b128 v[228:231], v210 offset:6144
	ds_read_b128 v[232:235], v210 offset:7168
	global_load_lds_dwordx4 v[198:199], off
	v_lshl_add_u64 v[198:199], s[24:25], 0, v[142:143]
	s_add_i32 m0, s52, 0xe000
	s_nop 0
	global_load_lds_dwordx4 v[198:199], off
	s_waitcnt vmcnt(8)
	s_waitcnt lgkmcnt(0)
	s_barrier
	s_waitcnt lgkmcnt(0)
	v_mfma_f32_16x16x32_bf16 v[132:135], v[144:147], v[190:193], v[132:135]
	v_mfma_f32_16x16x32_bf16 v[128:131], v[152:155], v[190:193], v[128:131]
	v_mfma_f32_16x16x32_bf16 v[116:119], v[144:147], v[212:215], v[116:119]
	v_mfma_f32_16x16x32_bf16 v[112:115], v[152:155], v[212:215], v[112:115]
	s_setprio 1
	v_mfma_f32_16x16x32_bf16 v[100:103], v[144:147], v[220:223], v[100:103]
	v_mfma_f32_16x16x32_bf16 v[96:99], v[152:155], v[220:223], v[96:99]
	v_mfma_f32_16x16x32_bf16 v[84:87], v[144:147], v[228:231], v[84:87]
	v_mfma_f32_16x16x32_bf16 v[80:83], v[152:155], v[228:231], v[80:83]
	v_mfma_f32_16x16x32_bf16 v[132:135], v[148:151], v[194:197], v[132:135]
	v_mfma_f32_16x16x32_bf16 v[128:131], v[156:159], v[194:197], v[128:131]
	v_mfma_f32_16x16x32_bf16 v[116:119], v[148:151], v[216:219], v[116:119]
	v_mfma_f32_16x16x32_bf16 v[112:115], v[156:159], v[216:219], v[112:115]
	v_mfma_f32_16x16x32_bf16 v[100:103], v[148:151], v[224:227], v[100:103]
	v_mfma_f32_16x16x32_bf16 v[96:99], v[156:159], v[224:227], v[96:99]
	v_mfma_f32_16x16x32_bf16 v[84:87], v[148:151], v[232:235], v[84:87]
	v_mfma_f32_16x16x32_bf16 v[80:83], v[156:159], v[232:235], v[80:83]
	v_mfma_f32_16x16x32_bf16 v[124:127], v[160:163], v[190:193], v[124:127]
	v_mfma_f32_16x16x32_bf16 v[120:123], v[182:185], v[190:193], v[120:123]
	v_mfma_f32_16x16x32_bf16 v[108:111], v[160:163], v[212:215], v[108:111]
	v_mfma_f32_16x16x32_bf16 v[104:107], v[182:185], v[212:215], v[104:107]
	v_mfma_f32_16x16x32_bf16 v[92:95], v[160:163], v[220:223], v[92:95]
	v_mfma_f32_16x16x32_bf16 v[88:91], v[182:185], v[220:223], v[88:91]
	v_mfma_f32_16x16x32_bf16 v[76:79], v[160:163], v[228:231], v[76:79]
	v_mfma_f32_16x16x32_bf16 v[72:75], v[182:185], v[228:231], v[72:75]
	v_mfma_f32_16x16x32_bf16 v[124:127], v[178:181], v[194:197], v[124:127]
	v_mfma_f32_16x16x32_bf16 v[120:123], v[186:189], v[194:197], v[120:123]
	v_mfma_f32_16x16x32_bf16 v[108:111], v[178:181], v[216:219], v[108:111]
	v_mfma_f32_16x16x32_bf16 v[104:107], v[186:189], v[216:219], v[104:107]
	s_barrier
	v_mfma_f32_16x16x32_bf16 v[92:95], v[178:181], v[224:227], v[92:95]
	v_mfma_f32_16x16x32_bf16 v[88:91], v[186:189], v[224:227], v[88:91]
	v_mfma_f32_16x16x32_bf16 v[76:79], v[178:181], v[232:235], v[76:79]
	v_mfma_f32_16x16x32_bf16 v[72:75], v[186:189], v[232:235], v[72:75]
	s_setprio 0
	s_add_i32 s18, s18, s41
	v_lshl_add_u64 v[198:199], s[16:17], 0, v[0:1]
	s_mov_b32 m0, s18
	ds_read_b128 v[190:193], v210 offset:16384
	ds_read_b128 v[194:197], v210 offset:17408
	ds_read_b128 v[212:215], v210 offset:18432
	ds_read_b128 v[216:219], v210 offset:19456
	ds_read_b128 v[220:223], v210 offset:20480
	ds_read_b128 v[224:227], v210 offset:21504
	ds_read_b128 v[228:231], v210 offset:22528
	ds_read_b128 v[232:235], v210 offset:23552
	global_load_lds_dwordx4 v[198:199], off
	s_add_i32 m0, s18, 0x2000
	v_lshl_add_u64 v[236:237], s[16:17], 0, v[2:3]
	s_add_u32 s16, s16, s12
	s_addc_u32 s17, s17, 0
	s_add_i32 s18, s19, s41
	global_load_lds_dwordx4 v[236:237], off
	v_lshl_add_u64 v[238:239], s[16:17], 0, v[0:1]
	s_mov_b32 m0, s18
	v_lshl_add_u64 v[240:241], s[16:17], 0, v[2:3]
	global_load_lds_dwordx4 v[238:239], off
	s_add_i32 m0, s18, 0x2000
	v_lshl_add_u64 v[242:243], s[28:29], 0, v[0:1]
	global_load_lds_dwordx4 v[240:241], off
	v_lshl_add_u64 v[244:245], s[28:29], 0, v[2:3]
	s_waitcnt vmcnt(6)
	s_waitcnt lgkmcnt(0)
	s_barrier
	s_waitcnt lgkmcnt(0)
	v_mfma_f32_16x16x32_bf16 v[68:71], v[144:147], v[190:193], v[68:71]
	v_mfma_f32_16x16x32_bf16 v[64:67], v[152:155], v[190:193], v[64:67]
	v_mfma_f32_16x16x32_bf16 v[52:55], v[144:147], v[212:215], v[52:55]
	s_mov_b32 m0, s52
	v_mfma_f32_16x16x32_bf16 v[48:51], v[152:155], v[212:215], v[48:51]
	s_setprio 1
	global_load_lds_dwordx4 v[242:243], off
	v_mfma_f32_16x16x32_bf16 v[36:39], v[144:147], v[220:223], v[36:39]
	v_mfma_f32_16x16x32_bf16 v[32:35], v[152:155], v[220:223], v[32:35]
	v_mfma_f32_16x16x32_bf16 v[20:23], v[144:147], v[228:231], v[20:23]
	v_mfma_f32_16x16x32_bf16 v[16:19], v[152:155], v[228:231], v[16:19]
	v_mfma_f32_16x16x32_bf16 v[68:71], v[148:151], v[194:197], v[68:71]
	v_mfma_f32_16x16x32_bf16 v[64:67], v[156:159], v[194:197], v[64:67]
	v_mfma_f32_16x16x32_bf16 v[52:55], v[148:151], v[216:219], v[52:55]
	s_mov_b32 m0, s53
	v_mfma_f32_16x16x32_bf16 v[48:51], v[156:159], v[216:219], v[48:51]
	global_load_lds_dwordx4 v[244:245], off
	v_mfma_f32_16x16x32_bf16 v[36:39], v[148:151], v[224:227], v[36:39]
	v_mfma_f32_16x16x32_bf16 v[32:35], v[156:159], v[224:227], v[32:35]
	v_mfma_f32_16x16x32_bf16 v[20:23], v[148:151], v[232:235], v[20:23]
	v_mfma_f32_16x16x32_bf16 v[16:19], v[156:159], v[232:235], v[16:19]
	v_mfma_f32_16x16x32_bf16 v[60:63], v[160:163], v[190:193], v[60:63]
	v_mfma_f32_16x16x32_bf16 v[56:59], v[182:185], v[190:193], v[56:59]
	v_mfma_f32_16x16x32_bf16 v[44:47], v[160:163], v[212:215], v[44:47]
	v_mfma_f32_16x16x32_bf16 v[40:43], v[182:185], v[212:215], v[40:43]
	v_mfma_f32_16x16x32_bf16 v[28:31], v[160:163], v[220:223], v[28:31]
	v_mfma_f32_16x16x32_bf16 v[24:27], v[182:185], v[220:223], v[24:27]
	v_mfma_f32_16x16x32_bf16 v[12:15], v[160:163], v[228:231], v[12:15]
	v_mfma_f32_16x16x32_bf16 v[8:11], v[182:185], v[228:231], v[8:11]
	v_mfma_f32_16x16x32_bf16 v[60:63], v[178:181], v[194:197], v[60:63]
	v_mfma_f32_16x16x32_bf16 v[56:59], v[186:189], v[194:197], v[56:59]
	v_mfma_f32_16x16x32_bf16 v[44:47], v[178:181], v[216:219], v[44:47]
	v_mfma_f32_16x16x32_bf16 v[40:43], v[186:189], v[216:219], v[40:43]
	s_barrier
; #define PG8_STAGE(bufoff, gbase, voff) do { _Pragma("unroll") for (int _i = 0; _i < 2; ++_i) \
;         __builtin_amdgcn_global_load_lds((const unsigned*)((const char*)(gbase) + (voff)[_i]), (PG8_LAS unsigned*)(lds + (bufoff) + ldsw + _i * 8192), 16, 0, 0); } while (0)
; #define PG8_LDA(dst, b, h) do { _Pragma("unroll") for (int m = 0; m < 4; ++m) _Pragma("unroll") for (int k = 0; k < 2; ++k) dst[m][k] = *(const PG8_LAS bf16x8*)(lds + PG8_SA(b, h) + aoff + m * 2048 + k * 1024); } while (0)
; #define PG8_LDB(dst, b, h) do { _Pragma("unroll") for (int n = 0; n < 2; ++n) _Pragma("unroll") for (int k = 0; k < 2; ++k) dst[n][k] = *(const PG8_LAS bf16x8*)(lds + PG8_SB(b, h) + boff + n * 2048 + k * 1024); } while (0)
; #define PG8_MMA(ai, bj, At, Bt) do { __builtin_amdgcn_s_setprio(1); _Pragma("unroll") for (int m = 0; m < 4; ++m) _Pragma("unroll") for (int n = 0; n < 2; ++n) _Pragma("unroll") for (int k = 0; k < 2; ++k) \
;         acc[ai][bj][m][n] = __builtin_amdgcn_mfma_f32_16x16x32_bf16(Bt[n][k], At[m][k], acc[ai][bj][m][n], 0, 0, 0); __builtin_amdgcn_s_setprio(0); } while (0)
; #define PG8_WAIT_V(n) asm volatile("s_waitcnt vmcnt(" #n ")" ::: "memory")
; #define PG8_WAIT_L(n) asm volatile("s_waitcnt lgkmcnt(" #n ")" ::: "memory")
; #define PG8_BAR __builtin_amdgcn_s_barrier()
; #define PG8_SCHED __builtin_amdgcn_sched_barrier(0)
; template <class Epi, class Sched, bool ALIGN_EPI = false, bool SP2 = false>
; __device__ __forceinline__ void gemm_phase(PG8_LAS unsigned char* lds, const Gemm g, const Sched& S, const Epi& E) {
;     ...
;             PG8_WAIT_V(8); PG8_WAIT_L(0); PG8_BAR; PG8_MMA(1, 0, At, B0); PG8_MMA(1, 1, At, B1); PG8_BAR; PG8_SCHED;
;             PG8_LDB(B0, 1, 0); PG8_LDB(B1, 1, 1); PG8_SCHED; PG8_LDA(At, 1, 0); PG8_STAGE(PG8_SA(0, 1), a2 + hstep, voffA);
;             PG8_WAIT_V(8); PG8_WAIT_L(0); PG8_BAR; PG8_MMA(0, 0, At, B0); PG8_MMA(0, 1, At, B1); PG8_BAR; PG8_SCHED;
	v_mfma_f32_16x16x32_bf16 v[28:31], v[178:181], v[224:227], v[28:31]
	v_mfma_f32_16x16x32_bf16 v[24:27], v[186:189], v[224:227], v[24:27]
	v_mfma_f32_16x16x32_bf16 v[12:15], v[178:181], v[232:235], v[12:15]
	v_mfma_f32_16x16x32_bf16 v[8:11], v[186:189], v[232:235], v[8:11]
	s_setprio 0
	s_add_i32 s18, 0, 0x18000
	v_add_u32_e32 v137, s18, v200
	ds_read_b128 v[144:147], v137
	ds_read_b128 v[148:151], v137 offset:1024
	ds_read_b128 v[152:155], v137 offset:2048
	ds_read_b128 v[156:159], v137 offset:3072
	v_add_u32_e32 v137, s33, v200
	ds_read_b128 v[160:163], v137
	ds_read_b128 v[178:181], v137 offset:1024
	ds_read_b128 v[182:185], v137 offset:2048
	ds_read_b128 v[186:189], v137 offset:3072
	s_add_u32 s16, s28, s12
	s_addc_u32 s17, s29, 0
	s_mov_b32 m0, s54
	v_lshl_add_u64 v[246:247], s[16:17], 0, v[0:1]
	ds_read_b128 v[190:193], v210 offset:32768
	ds_read_b128 v[194:197], v210 offset:33792
	ds_read_b128 v[212:215], v210 offset:34816
	ds_read_b128 v[216:219], v210 offset:35840
	ds_read_b128 v[220:223], v210 offset:36864
	ds_read_b128 v[224:227], v210 offset:37888
	ds_read_b128 v[228:231], v210 offset:38912
	ds_read_b128 v[232:235], v210 offset:39936
	global_load_lds_dwordx4 v[246:247], off
	v_lshl_add_u64 v[246:247], s[16:17], 0, v[2:3]
	s_mov_b32 m0, s55
	s_nop 0
	global_load_lds_dwordx4 v[246:247], off
	s_waitcnt vmcnt(8)
	s_waitcnt lgkmcnt(0)
	s_barrier
	s_waitcnt lgkmcnt(0)
	v_mfma_f32_16x16x32_bf16 v[132:135], v[144:147], v[190:193], v[132:135]
	v_mfma_f32_16x16x32_bf16 v[128:131], v[152:155], v[190:193], v[128:131]
	v_mfma_f32_16x16x32_bf16 v[116:119], v[144:147], v[212:215], v[116:119]
	v_mfma_f32_16x16x32_bf16 v[112:115], v[152:155], v[212:215], v[112:115]
	s_setprio 1
	v_mfma_f32_16x16x32_bf16 v[100:103], v[144:147], v[220:223], v[100:103]
	v_mfma_f32_16x16x32_bf16 v[96:99], v[152:155], v[220:223], v[96:99]
	v_mfma_f32_16x16x32_bf16 v[84:87], v[144:147], v[228:231], v[84:87]
	v_mfma_f32_16x16x32_bf16 v[80:83], v[152:155], v[228:231], v[80:83]
	v_mfma_f32_16x16x32_bf16 v[132:135], v[148:151], v[194:197], v[132:135]
	v_mfma_f32_16x16x32_bf16 v[128:131], v[156:159], v[194:197], v[128:131]
	v_mfma_f32_16x16x32_bf16 v[116:119], v[148:151], v[216:219], v[116:119]
	v_mfma_f32_16x16x32_bf16 v[112:115], v[156:159], v[216:219], v[112:115]
	v_mfma_f32_16x16x32_bf16 v[100:103], v[148:151], v[224:227], v[100:103]
	v_mfma_f32_16x16x32_bf16 v[96:99], v[156:159], v[224:227], v[96:99]
	v_mfma_f32_16x16x32_bf16 v[84:87], v[148:151], v[232:235], v[84:87]
	v_mfma_f32_16x16x32_bf16 v[80:83], v[156:159], v[232:235], v[80:83]
	v_mfma_f32_16x16x32_bf16 v[124:127], v[160:163], v[190:193], v[124:127]
	v_mfma_f32_16x16x32_bf16 v[120:123], v[182:185], v[190:193], v[120:123]
	v_mfma_f32_16x16x32_bf16 v[108:111], v[160:163], v[212:215], v[108:111]
	v_mfma_f32_16x16x32_bf16 v[104:107], v[182:185], v[212:215], v[104:107]
	v_mfma_f32_16x16x32_bf16 v[92:95], v[160:163], v[220:223], v[92:95]
	v_mfma_f32_16x16x32_bf16 v[88:91], v[182:185], v[220:223], v[88:91]
	v_mfma_f32_16x16x32_bf16 v[76:79], v[160:163], v[228:231], v[76:79]
	v_mfma_f32_16x16x32_bf16 v[72:75], v[182:185], v[228:231], v[72:75]
	v_mfma_f32_16x16x32_bf16 v[124:127], v[178:181], v[194:197], v[124:127]
	v_mfma_f32_16x16x32_bf16 v[120:123], v[186:189], v[194:197], v[120:123]
	v_mfma_f32_16x16x32_bf16 v[108:111], v[178:181], v[216:219], v[108:111]
	v_mfma_f32_16x16x32_bf16 v[104:107], v[186:189], v[216:219], v[104:107]
	s_barrier
; #define PG8_STAGE(bufoff, gbase, voff) do { _Pragma("unroll") for (int _i = 0; _i < 2; ++_i) \
;         __builtin_amdgcn_global_load_lds((const unsigned*)((const char*)(gbase) + (voff)[_i]), (PG8_LAS unsigned*)(lds + (bufoff) + ldsw + _i * 8192), 16, 0, 0); } while (0)
; #define PG8_LDA(dst, b, h) do { _Pragma("unroll") for (int m = 0; m < 4; ++m) _Pragma("unroll") for (int k = 0; k < 2; ++k) dst[m][k] = *(const PG8_LAS bf16x8*)(lds + PG8_SA(b, h) + aoff + m * 2048 + k * 1024); } while (0)
; #define PG8_MMA(ai, bj, At, Bt) do { __builtin_amdgcn_s_setprio(1); _Pragma("unroll") for (int m = 0; m < 4; ++m) _Pragma("unroll") for (int n = 0; n < 2; ++n) _Pragma("unroll") for (int k = 0; k < 2; ++k) \
;         acc[ai][bj][m][n] = __builtin_amdgcn_mfma_f32_16x16x32_bf16(Bt[n][k], At[m][k], acc[ai][bj][m][n], 0, 0, 0); __builtin_amdgcn_s_setprio(0); } while (0)
; #define PG8_WAIT_V(n) asm volatile("s_waitcnt vmcnt(" #n ")" ::: "memory")
; #define PG8_WAIT_L(n) asm volatile("s_waitcnt lgkmcnt(" #n ")" ::: "memory")
; #define PG8_BAR __builtin_amdgcn_s_barrier()
; #define PG8_SCHED __builtin_amdgcn_sched_barrier(0)
; template <class Epi, class Sched, bool ALIGN_EPI = false, bool SP2 = false>
; __device__ __forceinline__ void gemm_phase(PG8_LAS unsigned char* lds, const Gemm g, const Sched& S, const Epi& E) {
;     ...
;         for (int t = 0; t < nt; t += 2) {
;             const bool last = (t == nt - 2);
;             const char* a1 = cA + (size_t)(t + 1) * kstep;
;             const char* a2 = last ? nA : cA + (size_t)(t + 2) * kstep; const char* b2 = last ? nB : cB + (size_t)(t + 2) * kstep;
;             const char* a3 = a2 + kstep; const char* b3 = b2 + kstep;
;     ...
;             PG8_WAIT_V(8); PG8_WAIT_L(0); PG8_BAR; PG8_MMA(0, 0, At, B0); PG8_MMA(0, 1, At, B1); PG8_BAR; PG8_SCHED;
;             PG8_LDA(At, 1, 1); PG8_STAGE(PG8_SB(1, 0), b3, voffB); PG8_STAGE(PG8_SB(1, 1), b3 + hstep, voffB); PG8_STAGE(PG8_SA(1, 0), a3, voffA);
;             PG8_WAIT_V(8); PG8_WAIT_L(0); PG8_BAR; PG8_MMA(1, 0, At, B0); PG8_MMA(1, 1, At, B1); PG8_BAR; PG8_SCHED;
	v_mfma_f32_16x16x32_bf16 v[92:95], v[178:181], v[224:227], v[92:95]
	v_mfma_f32_16x16x32_bf16 v[88:91], v[186:189], v[224:227], v[88:91]
	v_mfma_f32_16x16x32_bf16 v[76:79], v[178:181], v[232:235], v[76:79]
	v_mfma_f32_16x16x32_bf16 v[72:75], v[186:189], v[232:235], v[72:75]
	s_setprio 0
	s_add_i32 s16, s18, s41
	v_lshl_add_u64 v[198:199], v[198:199], 0, s[20:21]
	s_mov_b32 m0, s16
	ds_read_b128 v[190:193], v210 offset:49152
	ds_read_b128 v[194:197], v210 offset:50176
	ds_read_b128 v[212:215], v210 offset:51200
	ds_read_b128 v[216:219], v210 offset:52224
	ds_read_b128 v[220:223], v210 offset:53248
	ds_read_b128 v[224:227], v210 offset:54272
	ds_read_b128 v[228:231], v210 offset:55296
	ds_read_b128 v[232:235], v210 offset:56320
	global_load_lds_dwordx4 v[198:199], off
	v_lshl_add_u64 v[198:199], v[236:237], 0, s[20:21]
	s_add_i32 m0, s16, 0x2000
	s_add_i32 s16, s33, s41
	global_load_lds_dwordx4 v[198:199], off
	v_lshl_add_u64 v[198:199], v[238:239], 0, s[20:21]
	s_mov_b32 m0, s16
	s_nop 0
	global_load_lds_dwordx4 v[198:199], off
	v_lshl_add_u64 v[198:199], v[240:241], 0, s[20:21]
	s_add_i32 m0, s16, 0x2000
	s_nop 0
	global_load_lds_dwordx4 v[198:199], off
	v_lshl_add_u64 v[198:199], v[242:243], 0, s[20:21]
	v_lshl_add_u64 v[244:245], v[244:245], 0, s[20:21]
	s_waitcnt vmcnt(6)
	s_waitcnt lgkmcnt(0)
	s_barrier
	s_waitcnt lgkmcnt(0)
	v_mfma_f32_16x16x32_bf16 v[68:71], v[144:147], v[190:193], v[68:71]
	v_mfma_f32_16x16x32_bf16 v[64:67], v[152:155], v[190:193], v[64:67]
	v_mfma_f32_16x16x32_bf16 v[52:55], v[144:147], v[212:215], v[52:55]
	s_mov_b32 m0, s56
	v_mfma_f32_16x16x32_bf16 v[48:51], v[152:155], v[212:215], v[48:51]
	s_setprio 1
	global_load_lds_dwordx4 v[198:199], off
	v_mfma_f32_16x16x32_bf16 v[36:39], v[144:147], v[220:223], v[36:39]
	v_mfma_f32_16x16x32_bf16 v[32:35], v[152:155], v[220:223], v[32:35]
	v_mfma_f32_16x16x32_bf16 v[20:23], v[144:147], v[228:231], v[20:23]
	s_add_u32 s24, s24, 0x100
	s_addc_u32 s25, s25, 0
	v_mfma_f32_16x16x32_bf16 v[16:19], v[152:155], v[228:231], v[16:19]
	s_add_u32 s23, s23, 0x100
	s_addc_u32 s35, s35, 0
	v_mfma_f32_16x16x32_bf16 v[68:71], v[148:151], v[194:197], v[68:71]
	s_add_u32 s16, s24, 0x80
	s_addc_u32 s17, s25, 0
	v_mfma_f32_16x16x32_bf16 v[64:67], v[156:159], v[194:197], v[64:67]
	s_cmp_eq_u32 s60, s36
	s_cselect_b32 s29, s3, s17
	s_cselect_b32 s28, s2, s16
	v_mfma_f32_16x16x32_bf16 v[52:55], v[148:151], v[216:219], v[52:55]
	s_cselect_b32 s17, s9, s35
	s_cselect_b32 s16, s8, s23
	s_mov_b32 m0, s57
	v_mfma_f32_16x16x32_bf16 v[48:51], v[156:159], v[216:219], v[48:51]
	s_add_i32 s36, s36, 2
	global_load_lds_dwordx4 v[244:245], off
	v_mfma_f32_16x16x32_bf16 v[36:39], v[148:151], v[224:227], v[36:39]
	v_mfma_f32_16x16x32_bf16 v[32:35], v[156:159], v[224:227], v[32:35]
	v_mfma_f32_16x16x32_bf16 v[20:23], v[148:151], v[232:235], v[20:23]
	v_mfma_f32_16x16x32_bf16 v[16:19], v[156:159], v[232:235], v[16:19]
	v_mfma_f32_16x16x32_bf16 v[60:63], v[160:163], v[190:193], v[60:63]
	v_mfma_f32_16x16x32_bf16 v[56:59], v[182:185], v[190:193], v[56:59]
	v_mfma_f32_16x16x32_bf16 v[44:47], v[160:163], v[212:215], v[44:47]
	v_mfma_f32_16x16x32_bf16 v[40:43], v[182:185], v[212:215], v[40:43]
	v_mfma_f32_16x16x32_bf16 v[28:31], v[160:163], v[220:223], v[28:31]
	v_mfma_f32_16x16x32_bf16 v[24:27], v[182:185], v[220:223], v[24:27]
	v_mfma_f32_16x16x32_bf16 v[12:15], v[160:163], v[228:231], v[12:15]
	v_mfma_f32_16x16x32_bf16 v[8:11], v[182:185], v[228:231], v[8:11]
	v_mfma_f32_16x16x32_bf16 v[60:63], v[178:181], v[194:197], v[60:63]
	v_mfma_f32_16x16x32_bf16 v[56:59], v[186:189], v[194:197], v[56:59]
	v_mfma_f32_16x16x32_bf16 v[44:47], v[178:181], v[216:219], v[44:47]
	v_mfma_f32_16x16x32_bf16 v[40:43], v[186:189], v[216:219], v[40:43]
	s_barrier
	v_mfma_f32_16x16x32_bf16 v[28:31], v[178:181], v[224:227], v[28:31]
	v_mfma_f32_16x16x32_bf16 v[24:27], v[186:189], v[224:227], v[24:27]
	v_mfma_f32_16x16x32_bf16 v[12:15], v[178:181], v[232:235], v[12:15]
	v_mfma_f32_16x16x32_bf16 v[8:11], v[186:189], v[232:235], v[8:11]
	s_setprio 0
	s_add_i32 s18, s59, 2
	s_cmp_ge_u32 s36, s18
	s_cbranch_scc0 .LBB0_203
	s_and_b64 vcc, exec, s[46:47]
	s_cbranch_vccz .LBB0_206
	s_barrier
	s_setprio 1

; #define PG8_STAGE(bufoff, gbase, voff) do { _Pragma("unroll") for (int _i = 0; _i < 2; ++_i) \
;         __builtin_amdgcn_global_load_lds((const unsigned*)((const char*)(gbase) + (voff)[_i]), (PG8_LAS unsigned*)(lds + (bufoff) + ldsw + _i * 8192), 16, 0, 0); } while (0)
; #define PG8_LDA(dst, b, h) do { _Pragma("unroll") for (int m = 0; m < 4; ++m) _Pragma("unroll") for (int k = 0; k < 2; ++k) dst[m][k] = *(const PG8_LAS bf16x8*)(lds + PG8_SA(b, h) + aoff + m * 2048 + k * 1024); } while (0)
; #define PG8_LDB(dst, b, h) do { _Pragma("unroll") for (int n = 0; n < 2; ++n) _Pragma("unroll") for (int k = 0; k < 2; ++k) dst[n][k] = *(const PG8_LAS bf16x8*)(lds + PG8_SB(b, h) + boff + n * 2048 + k * 1024); } while (0)
; #define PG8_MMA(ai, bj, At, Bt) do { __builtin_amdgcn_s_setprio(1); _Pragma("unroll") for (int m = 0; m < 4; ++m) _Pragma("unroll") for (int n = 0; n < 2; ++n) _Pragma("unroll") for (int k = 0; k < 2; ++k) \
;         acc[ai][bj][m][n] = __builtin_amdgcn_mfma_f32_16x16x32_bf16(Bt[n][k], At[m][k], acc[ai][bj][m][n], 0, 0, 0); __builtin_amdgcn_s_setprio(0); } while (0)
; #define PG8_WAIT_V(n) asm volatile("s_waitcnt vmcnt(" #n ")" ::: "memory")
; #define PG8_WAIT_L(n) asm volatile("s_waitcnt lgkmcnt(" #n ")" ::: "memory")
; #define PG8_BAR __builtin_amdgcn_s_barrier()
; #define PG8_SCHED __builtin_amdgcn_sched_barrier(0)
; template <class Epi, class Sched, bool ALIGN_EPI = false, bool SP2 = false>
; __device__ __forceinline__ void gemm_phase(PG8_LAS unsigned char* lds, const Gemm g, const Sched& S, const Epi& E) {
;     ...
;             PG8_LDB(B0, 0, 0); PG8_LDB(B1, 0, 1); PG8_SCHED; PG8_LDA(At, 0, 0); PG8_STAGE(PG8_SA(1, 1), a1 + hstep, voffA);
;             PG8_WAIT_V(8); PG8_WAIT_L(0); PG8_BAR; PG8_MMA(0, 0, At, B0); PG8_MMA(0, 1, At, B1); PG8_BAR; PG8_SCHED;
;             PG8_LDA(At, 0, 1); PG8_STAGE(PG8_SB(0, 0), b2, voffB); PG8_STAGE(PG8_SB(0, 1), b2 + hstep, voffB); PG8_STAGE(PG8_SA(0, 0), a2, voffA);
;             PG8_WAIT_V(8); PG8_WAIT_L(0); PG8_BAR; PG8_MMA(1, 0, At, B0); PG8_MMA(1, 1, At, B1); PG8_BAR; PG8_SCHED;
.LBB0_257:
	s_add_i32 s18, 0, 0x10000
	v_add_u32_e32 v0, s18, v210
	s_add_i32 s19, 0, 0x14000
	ds_read_b128 v[104:107], v0
	ds_read_b128 v[140:143], v0 offset:1024
	ds_read_b128 v[144:147], v0 offset:2048
	ds_read_b128 v[148:151], v0 offset:3072
	v_add_u32_e32 v0, s19, v210
	ds_read_b128 v[152:155], v0
	ds_read_b128 v[156:159], v0 offset:1024
	ds_read_b128 v[160:163], v0 offset:2048
	ds_read_b128 v[192:195], v0 offset:3072
	v_lshl_add_u64 v[2:3], s[8:9], 0, v[188:189]
	s_add_i32 m0, s44, 0xc000
	ds_read_b128 v[196:199], v212
	ds_read_b128 v[214:217], v212 offset:1024
	ds_read_b128 v[218:221], v212 offset:2048
	ds_read_b128 v[222:225], v212 offset:3072
	ds_read_b128 v[226:229], v212 offset:4096
	ds_read_b128 v[230:233], v212 offset:5120
	ds_read_b128 v[234:237], v212 offset:6144
	ds_read_b128 v[238:241], v212 offset:7168
	global_load_lds_dwordx4 v[2:3], off
	v_lshl_add_u64 v[2:3], s[8:9], 0, v[190:191]
	s_add_i32 m0, s44, 0xe000
	s_nop 0
	global_load_lds_dwordx4 v[2:3], off
	s_waitcnt vmcnt(8)
	s_waitcnt lgkmcnt(0)
	s_barrier
	s_waitcnt lgkmcnt(0)
	v_mfma_f32_16x16x32_bf16 v[136:139], v[104:107], v[196:199], v[136:139]
	v_mfma_f32_16x16x32_bf16 v[128:131], v[144:147], v[196:199], v[128:131]
	v_mfma_f32_16x16x32_bf16 v[120:123], v[104:107], v[218:221], v[120:123]
	v_mfma_f32_16x16x32_bf16 v[112:115], v[144:147], v[218:221], v[112:115]
	s_setprio 1
	v_mfma_f32_16x16x32_bf16 v[100:103], v[104:107], v[226:229], v[100:103]
	v_mfma_f32_16x16x32_bf16 v[92:95], v[144:147], v[226:229], v[92:95]
	v_mfma_f32_16x16x32_bf16 v[84:87], v[104:107], v[234:237], v[84:87]
	v_mfma_f32_16x16x32_bf16 v[76:79], v[144:147], v[234:237], v[76:79]
	v_mfma_f32_16x16x32_bf16 v[136:139], v[140:143], v[214:217], v[136:139]
	v_mfma_f32_16x16x32_bf16 v[128:131], v[148:151], v[214:217], v[128:131]
	v_mfma_f32_16x16x32_bf16 v[120:123], v[140:143], v[222:225], v[120:123]
	v_mfma_f32_16x16x32_bf16 v[112:115], v[148:151], v[222:225], v[112:115]
	v_mfma_f32_16x16x32_bf16 v[100:103], v[140:143], v[230:233], v[100:103]
	v_mfma_f32_16x16x32_bf16 v[92:95], v[148:151], v[230:233], v[92:95]
	v_mfma_f32_16x16x32_bf16 v[84:87], v[140:143], v[238:241], v[84:87]
	v_mfma_f32_16x16x32_bf16 v[76:79], v[148:151], v[238:241], v[76:79]
	v_mfma_f32_16x16x32_bf16 v[132:135], v[152:155], v[196:199], v[132:135]
	v_mfma_f32_16x16x32_bf16 v[124:127], v[160:163], v[196:199], v[124:127]
	v_mfma_f32_16x16x32_bf16 v[116:119], v[152:155], v[218:221], v[116:119]
	v_mfma_f32_16x16x32_bf16 v[108:111], v[160:163], v[218:221], v[108:111]
	v_mfma_f32_16x16x32_bf16 v[96:99], v[152:155], v[226:229], v[96:99]
	v_mfma_f32_16x16x32_bf16 v[88:91], v[160:163], v[226:229], v[88:91]
	v_mfma_f32_16x16x32_bf16 v[80:83], v[152:155], v[234:237], v[80:83]
	v_mfma_f32_16x16x32_bf16 v[72:75], v[160:163], v[234:237], v[72:75]
	v_mfma_f32_16x16x32_bf16 v[132:135], v[156:159], v[214:217], v[132:135]
	v_mfma_f32_16x16x32_bf16 v[124:127], v[192:195], v[214:217], v[124:127]
	v_mfma_f32_16x16x32_bf16 v[116:119], v[156:159], v[222:225], v[116:119]
	v_mfma_f32_16x16x32_bf16 v[108:111], v[192:195], v[222:225], v[108:111]
	s_barrier
	v_mfma_f32_16x16x32_bf16 v[96:99], v[156:159], v[230:233], v[96:99]
	v_mfma_f32_16x16x32_bf16 v[88:91], v[192:195], v[230:233], v[88:91]
	v_mfma_f32_16x16x32_bf16 v[80:83], v[156:159], v[238:241], v[80:83]
	v_mfma_f32_16x16x32_bf16 v[72:75], v[192:195], v[238:241], v[72:75]
	s_setprio 0
	s_add_i32 s16, s18, s36
	v_lshl_add_u64 v[2:3], s[40:41], 0, v[182:183]
	s_mov_b32 m0, s16
	ds_read_b128 v[196:199], v212 offset:16384
	ds_read_b128 v[214:217], v212 offset:17408
	ds_read_b128 v[218:221], v212 offset:18432
	ds_read_b128 v[222:225], v212 offset:19456
	ds_read_b128 v[226:229], v212 offset:20480
	ds_read_b128 v[230:233], v212 offset:21504
	ds_read_b128 v[234:237], v212 offset:22528
	ds_read_b128 v[238:241], v212 offset:23552
	global_load_lds_dwordx4 v[2:3], off
	s_add_i32 m0, s16, 0x2000
	s_add_u32 s16, s40, 0x40000
	v_lshl_add_u64 v[200:201], s[40:41], 0, v[178:179]
	s_addc_u32 s17, s41, 0
	s_add_i32 s18, s19, s36
	global_load_lds_dwordx4 v[200:201], off
	v_lshl_add_u64 v[242:243], s[16:17], 0, v[182:183]
	s_mov_b32 m0, s18
	v_lshl_add_u64 v[244:245], s[42:43], 0, v[180:181]
	global_load_lds_dwordx4 v[242:243], off
	v_lshl_add_u64 v[242:243], s[16:17], 0, v[178:179]
	s_add_i32 m0, s18, 0x2000
	s_nop 0
	global_load_lds_dwordx4 v[242:243], off
	v_lshl_add_u64 v[242:243], s[42:43], 0, v[184:185]
	s_waitcnt vmcnt(6)
	s_waitcnt lgkmcnt(0)
	s_barrier
	s_waitcnt lgkmcnt(0)
	v_mfma_f32_16x16x32_bf16 v[68:71], v[104:107], v[196:199], v[68:71]
	v_mfma_f32_16x16x32_bf16 v[60:63], v[144:147], v[196:199], v[60:63]
	v_mfma_f32_16x16x32_bf16 v[52:55], v[104:107], v[218:221], v[52:55]
	s_mov_b32 m0, s44
	v_mfma_f32_16x16x32_bf16 v[44:47], v[144:147], v[218:221], v[44:47]
	s_setprio 1
	global_load_lds_dwordx4 v[242:243], off
	v_mfma_f32_16x16x32_bf16 v[36:39], v[104:107], v[226:229], v[36:39]
	v_mfma_f32_16x16x32_bf16 v[28:31], v[144:147], v[226:229], v[28:31]
	v_mfma_f32_16x16x32_bf16 v[20:23], v[104:107], v[234:237], v[20:23]
	v_mfma_f32_16x16x32_bf16 v[12:15], v[144:147], v[234:237], v[12:15]
	v_mfma_f32_16x16x32_bf16 v[68:71], v[140:143], v[214:217], v[68:71]
	v_mfma_f32_16x16x32_bf16 v[60:63], v[148:151], v[214:217], v[60:63]
	v_mfma_f32_16x16x32_bf16 v[52:55], v[140:143], v[222:225], v[52:55]
	s_mov_b32 m0, s45
	v_mfma_f32_16x16x32_bf16 v[44:47], v[148:151], v[222:225], v[44:47]
	global_load_lds_dwordx4 v[244:245], off
	v_mfma_f32_16x16x32_bf16 v[36:39], v[140:143], v[230:233], v[36:39]
	v_mfma_f32_16x16x32_bf16 v[28:31], v[148:151], v[230:233], v[28:31]
	v_mfma_f32_16x16x32_bf16 v[20:23], v[140:143], v[238:241], v[20:23]
	v_mfma_f32_16x16x32_bf16 v[12:15], v[148:151], v[238:241], v[12:15]
	v_mfma_f32_16x16x32_bf16 v[64:67], v[152:155], v[196:199], v[64:67]
	v_mfma_f32_16x16x32_bf16 v[56:59], v[160:163], v[196:199], v[56:59]
	v_mfma_f32_16x16x32_bf16 v[48:51], v[152:155], v[218:221], v[48:51]
	v_mfma_f32_16x16x32_bf16 v[40:43], v[160:163], v[218:221], v[40:43]
	v_mfma_f32_16x16x32_bf16 v[32:35], v[152:155], v[226:229], v[32:35]
	v_mfma_f32_16x16x32_bf16 v[24:27], v[160:163], v[226:229], v[24:27]
	v_mfma_f32_16x16x32_bf16 v[16:19], v[152:155], v[234:237], v[16:19]
	v_mfma_f32_16x16x32_bf16 v[8:11], v[160:163], v[234:237], v[8:11]
	v_mfma_f32_16x16x32_bf16 v[64:67], v[156:159], v[214:217], v[64:67]
	v_mfma_f32_16x16x32_bf16 v[56:59], v[192:195], v[214:217], v[56:59]
	v_mfma_f32_16x16x32_bf16 v[48:51], v[156:159], v[222:225], v[48:51]
	v_mfma_f32_16x16x32_bf16 v[40:43], v[192:195], v[222:225], v[40:43]
	s_barrier
; #define PG8_STAGE(bufoff, gbase, voff) do { _Pragma("unroll") for (int _i = 0; _i < 2; ++_i) \
;         __builtin_amdgcn_global_load_lds((const unsigned*)((const char*)(gbase) + (voff)[_i]), (PG8_LAS unsigned*)(lds + (bufoff) + ldsw + _i * 8192), 16, 0, 0); } while (0)
; #define PG8_LDA(dst, b, h) do { _Pragma("unroll") for (int m = 0; m < 4; ++m) _Pragma("unroll") for (int k = 0; k < 2; ++k) dst[m][k] = *(const PG8_LAS bf16x8*)(lds + PG8_SA(b, h) + aoff + m * 2048 + k * 1024); } while (0)
; #define PG8_LDB(dst, b, h) do { _Pragma("unroll") for (int n = 0; n < 2; ++n) _Pragma("unroll") for (int k = 0; k < 2; ++k) dst[n][k] = *(const PG8_LAS bf16x8*)(lds + PG8_SB(b, h) + boff + n * 2048 + k * 1024); } while (0)
; #define PG8_MMA(ai, bj, At, Bt) do { __builtin_amdgcn_s_setprio(1); _Pragma("unroll") for (int m = 0; m < 4; ++m) _Pragma("unroll") for (int n = 0; n < 2; ++n) _Pragma("unroll") for (int k = 0; k < 2; ++k) \
;         acc[ai][bj][m][n] = __builtin_amdgcn_mfma_f32_16x16x32_bf16(Bt[n][k], At[m][k], acc[ai][bj][m][n], 0, 0, 0); __builtin_amdgcn_s_setprio(0); } while (0)
; #define PG8_WAIT_V(n) asm volatile("s_waitcnt vmcnt(" #n ")" ::: "memory")
; #define PG8_WAIT_L(n) asm volatile("s_waitcnt lgkmcnt(" #n ")" ::: "memory")
; #define PG8_BAR __builtin_amdgcn_s_barrier()
; #define PG8_SCHED __builtin_amdgcn_sched_barrier(0)
; template <class Epi, class Sched, bool ALIGN_EPI = false, bool SP2 = false>
; __device__ __forceinline__ void gemm_phase(PG8_LAS unsigned char* lds, const Gemm g, const Sched& S, const Epi& E) {
;     ...
;             PG8_WAIT_V(8); PG8_WAIT_L(0); PG8_BAR; PG8_MMA(1, 0, At, B0); PG8_MMA(1, 1, At, B1); PG8_BAR; PG8_SCHED;
;             PG8_LDB(B0, 1, 0); PG8_LDB(B1, 1, 1); PG8_SCHED; PG8_LDA(At, 1, 0); PG8_STAGE(PG8_SA(0, 1), a2 + hstep, voffA);
;             PG8_WAIT_V(8); PG8_WAIT_L(0); PG8_BAR; PG8_MMA(0, 0, At, B0); PG8_MMA(0, 1, At, B1); PG8_BAR; PG8_SCHED;
	v_mfma_f32_16x16x32_bf16 v[32:35], v[156:159], v[230:233], v[32:35]
	v_mfma_f32_16x16x32_bf16 v[24:27], v[192:195], v[230:233], v[24:27]
	v_mfma_f32_16x16x32_bf16 v[16:19], v[156:159], v[238:241], v[16:19]
	v_mfma_f32_16x16x32_bf16 v[8:11], v[192:195], v[238:241], v[8:11]
	s_setprio 0
	s_add_i32 s18, 0, 0x18000
	v_add_u32_e32 v0, s18, v210
	ds_read_b128 v[104:107], v0
	ds_read_b128 v[140:143], v0 offset:1024
	ds_read_b128 v[144:147], v0 offset:2048
	ds_read_b128 v[148:151], v0 offset:3072
	v_add_u32_e32 v0, s33, v210
	ds_read_b128 v[152:155], v0
	ds_read_b128 v[156:159], v0 offset:1024
	ds_read_b128 v[160:163], v0 offset:2048
	ds_read_b128 v[192:195], v0 offset:3072
	s_add_u32 s16, s42, 0x40000
	s_addc_u32 s17, s43, 0
	s_mov_b32 m0, s46
	v_lshl_add_u64 v[246:247], s[16:17], 0, v[184:185]
	ds_read_b128 v[196:199], v212 offset:32768
	ds_read_b128 v[214:217], v212 offset:33792
	ds_read_b128 v[218:221], v212 offset:34816
	ds_read_b128 v[222:225], v212 offset:35840
	ds_read_b128 v[226:229], v212 offset:36864
	ds_read_b128 v[230:233], v212 offset:37888
	ds_read_b128 v[234:237], v212 offset:38912
	ds_read_b128 v[238:241], v212 offset:39936
	global_load_lds_dwordx4 v[246:247], off
	v_lshl_add_u64 v[246:247], s[16:17], 0, v[180:181]
	s_mov_b32 m0, s47
	s_nop 0
	global_load_lds_dwordx4 v[246:247], off
	s_waitcnt vmcnt(8)
	s_waitcnt lgkmcnt(0)
	s_barrier
	s_waitcnt lgkmcnt(0)
	v_mfma_f32_16x16x32_bf16 v[136:139], v[104:107], v[196:199], v[136:139]
	v_mfma_f32_16x16x32_bf16 v[128:131], v[144:147], v[196:199], v[128:131]
	v_mfma_f32_16x16x32_bf16 v[120:123], v[104:107], v[218:221], v[120:123]
	v_mfma_f32_16x16x32_bf16 v[112:115], v[144:147], v[218:221], v[112:115]
	s_setprio 1
	v_mfma_f32_16x16x32_bf16 v[100:103], v[104:107], v[226:229], v[100:103]
	v_mfma_f32_16x16x32_bf16 v[92:95], v[144:147], v[226:229], v[92:95]
	v_mfma_f32_16x16x32_bf16 v[84:87], v[104:107], v[234:237], v[84:87]
	v_mfma_f32_16x16x32_bf16 v[76:79], v[144:147], v[234:237], v[76:79]
	v_mfma_f32_16x16x32_bf16 v[136:139], v[140:143], v[214:217], v[136:139]
	v_mfma_f32_16x16x32_bf16 v[128:131], v[148:151], v[214:217], v[128:131]
	v_mfma_f32_16x16x32_bf16 v[120:123], v[140:143], v[222:225], v[120:123]
	v_mfma_f32_16x16x32_bf16 v[112:115], v[148:151], v[222:225], v[112:115]
	v_mfma_f32_16x16x32_bf16 v[100:103], v[140:143], v[230:233], v[100:103]
	v_mfma_f32_16x16x32_bf16 v[92:95], v[148:151], v[230:233], v[92:95]
	v_mfma_f32_16x16x32_bf16 v[84:87], v[140:143], v[238:241], v[84:87]
	v_mfma_f32_16x16x32_bf16 v[76:79], v[148:151], v[238:241], v[76:79]
	v_mfma_f32_16x16x32_bf16 v[132:135], v[152:155], v[196:199], v[132:135]
	v_mfma_f32_16x16x32_bf16 v[124:127], v[160:163], v[196:199], v[124:127]
	v_mfma_f32_16x16x32_bf16 v[116:119], v[152:155], v[218:221], v[116:119]
	v_mfma_f32_16x16x32_bf16 v[108:111], v[160:163], v[218:221], v[108:111]
	v_mfma_f32_16x16x32_bf16 v[96:99], v[152:155], v[226:229], v[96:99]
	v_mfma_f32_16x16x32_bf16 v[88:91], v[160:163], v[226:229], v[88:91]
	v_mfma_f32_16x16x32_bf16 v[80:83], v[152:155], v[234:237], v[80:83]
	v_mfma_f32_16x16x32_bf16 v[72:75], v[160:163], v[234:237], v[72:75]
	v_mfma_f32_16x16x32_bf16 v[132:135], v[156:159], v[214:217], v[132:135]
	v_mfma_f32_16x16x32_bf16 v[124:127], v[192:195], v[214:217], v[124:127]
	v_mfma_f32_16x16x32_bf16 v[116:119], v[156:159], v[222:225], v[116:119]
	v_mfma_f32_16x16x32_bf16 v[108:111], v[192:195], v[222:225], v[108:111]
	s_barrier
; #define PG8_STAGE(bufoff, gbase, voff) do { _Pragma("unroll") for (int _i = 0; _i < 2; ++_i) \
;         __builtin_amdgcn_global_load_lds((const unsigned*)((const char*)(gbase) + (voff)[_i]), (PG8_LAS unsigned*)(lds + (bufoff) + ldsw + _i * 8192), 16, 0, 0); } while (0)
; #define PG8_LDA(dst, b, h) do { _Pragma("unroll") for (int m = 0; m < 4; ++m) _Pragma("unroll") for (int k = 0; k < 2; ++k) dst[m][k] = *(const PG8_LAS bf16x8*)(lds + PG8_SA(b, h) + aoff + m * 2048 + k * 1024); } while (0)
; #define PG8_MMA(ai, bj, At, Bt) do { __builtin_amdgcn_s_setprio(1); _Pragma("unroll") for (int m = 0; m < 4; ++m) _Pragma("unroll") for (int n = 0; n < 2; ++n) _Pragma("unroll") for (int k = 0; k < 2; ++k) \
;         acc[ai][bj][m][n] = __builtin_amdgcn_mfma_f32_16x16x32_bf16(Bt[n][k], At[m][k], acc[ai][bj][m][n], 0, 0, 0); __builtin_amdgcn_s_setprio(0); } while (0)
; #define PG8_WAIT_V(n) asm volatile("s_waitcnt vmcnt(" #n ")" ::: "memory")
; #define PG8_WAIT_L(n) asm volatile("s_waitcnt lgkmcnt(" #n ")" ::: "memory")
; #define PG8_BAR __builtin_amdgcn_s_barrier()
; #define PG8_SCHED __builtin_amdgcn_sched_barrier(0)
; template <class Epi, class Sched, bool ALIGN_EPI = false, bool SP2 = false>
; __device__ __forceinline__ void gemm_phase(PG8_LAS unsigned char* lds, const Gemm g, const Sched& S, const Epi& E) {
;     ...
;         for (int t = 0; t < nt; t += 2) {
;             const bool last = (t == nt - 2);
;             const char* a1 = cA + (size_t)(t + 1) * kstep;
;             const char* a2 = last ? nA : cA + (size_t)(t + 2) * kstep; const char* b2 = last ? nB : cB + (size_t)(t + 2) * kstep;
;             const char* a3 = a2 + kstep; const char* b3 = b2 + kstep;
;     ...
;             PG8_WAIT_V(8); PG8_WAIT_L(0); PG8_BAR; PG8_MMA(0, 0, At, B0); PG8_MMA(0, 1, At, B1); PG8_BAR; PG8_SCHED;
;             PG8_LDA(At, 1, 1); PG8_STAGE(PG8_SB(1, 0), b3, voffB); PG8_STAGE(PG8_SB(1, 1), b3 + hstep, voffB); PG8_STAGE(PG8_SA(1, 0), a3, voffA);
;             PG8_WAIT_V(8); PG8_WAIT_L(0); PG8_BAR; PG8_MMA(1, 0, At, B0); PG8_MMA(1, 1, At, B1); PG8_BAR; PG8_SCHED;
	v_mfma_f32_16x16x32_bf16 v[96:99], v[156:159], v[230:233], v[96:99]
	v_mfma_f32_16x16x32_bf16 v[88:91], v[192:195], v[230:233], v[88:91]
	v_mfma_f32_16x16x32_bf16 v[80:83], v[156:159], v[238:241], v[80:83]
	v_mfma_f32_16x16x32_bf16 v[72:75], v[192:195], v[238:241], v[72:75]
	s_setprio 0
	s_add_i32 s16, s18, s36
	v_lshl_add_u64 v[2:3], v[2:3], 0, s[20:21]
	s_mov_b32 m0, s16
	ds_read_b128 v[196:199], v212 offset:49152
	ds_read_b128 v[214:217], v212 offset:50176
	ds_read_b128 v[218:221], v212 offset:51200
	ds_read_b128 v[222:225], v212 offset:52224
	ds_read_b128 v[226:229], v212 offset:53248
	ds_read_b128 v[230:233], v212 offset:54272
	ds_read_b128 v[234:237], v212 offset:55296
	ds_read_b128 v[238:241], v212 offset:56320
	global_load_lds_dwordx4 v[2:3], off
	s_add_i32 m0, s16, 0x2000
	s_add_u32 s16, s40, 0x40080
	v_lshl_add_u64 v[2:3], v[200:201], 0, s[20:21]
	s_addc_u32 s17, s41, 0
	s_add_i32 s18, s33, s36
	global_load_lds_dwordx4 v[2:3], off
	v_lshl_add_u64 v[2:3], s[16:17], 0, v[182:183]
	s_mov_b32 m0, s18
	s_nop 0
	global_load_lds_dwordx4 v[2:3], off
	v_lshl_add_u64 v[2:3], s[16:17], 0, v[178:179]
	s_add_i32 m0, s18, 0x2000
	s_nop 0
	global_load_lds_dwordx4 v[2:3], off
	v_lshl_add_u64 v[2:3], v[242:243], 0, s[20:21]
	v_lshl_add_u64 v[244:245], v[244:245], 0, s[20:21]
	s_waitcnt vmcnt(6)
	s_waitcnt lgkmcnt(0)
	s_barrier
	s_waitcnt lgkmcnt(0)
	v_mfma_f32_16x16x32_bf16 v[68:71], v[104:107], v[196:199], v[68:71]
	v_mfma_f32_16x16x32_bf16 v[60:63], v[144:147], v[196:199], v[60:63]
	v_mfma_f32_16x16x32_bf16 v[52:55], v[104:107], v[218:221], v[52:55]
	s_mov_b32 m0, s48
	v_mfma_f32_16x16x32_bf16 v[44:47], v[144:147], v[218:221], v[44:47]
	s_setprio 1
	global_load_lds_dwordx4 v[2:3], off
	v_mfma_f32_16x16x32_bf16 v[36:39], v[104:107], v[226:229], v[36:39]
	v_mfma_f32_16x16x32_bf16 v[28:31], v[144:147], v[226:229], v[28:31]
	v_mfma_f32_16x16x32_bf16 v[20:23], v[104:107], v[234:237], v[20:23]
	s_add_i32 s55, s55, 2
	v_mfma_f32_16x16x32_bf16 v[12:15], v[144:147], v[234:237], v[12:15]
	s_add_u32 s8, s8, 0x100
	s_addc_u32 s9, s9, 0
	v_mfma_f32_16x16x32_bf16 v[68:71], v[140:143], v[214:217], v[68:71]
	s_add_u32 s53, s53, 0x100
	s_addc_u32 s54, s54, 0
	v_mfma_f32_16x16x32_bf16 v[60:63], v[148:151], v[214:217], v[60:63]
	s_add_u32 s16, s8, 0xfffc0080
	s_addc_u32 s17, s9, -1
	v_mfma_f32_16x16x32_bf16 v[52:55], v[140:143], v[222:225], v[52:55]
	s_cmp_eq_u32 s55, 12
	s_cselect_b32 s43, s14, s17
	s_cselect_b32 s42, s15, s16
	s_mov_b32 m0, s49
	v_mfma_f32_16x16x32_bf16 v[44:47], v[148:151], v[222:225], v[44:47]
	s_cselect_b32 s41, s13, s54
	s_cselect_b32 s40, s25, s53
	global_load_lds_dwordx4 v[244:245], off
	v_mfma_f32_16x16x32_bf16 v[36:39], v[140:143], v[230:233], v[36:39]
	v_mfma_f32_16x16x32_bf16 v[28:31], v[148:151], v[230:233], v[28:31]
	v_mfma_f32_16x16x32_bf16 v[20:23], v[140:143], v[238:241], v[20:23]
	v_mfma_f32_16x16x32_bf16 v[12:15], v[148:151], v[238:241], v[12:15]
	v_mfma_f32_16x16x32_bf16 v[64:67], v[152:155], v[196:199], v[64:67]
	v_mfma_f32_16x16x32_bf16 v[56:59], v[160:163], v[196:199], v[56:59]
	v_mfma_f32_16x16x32_bf16 v[48:51], v[152:155], v[218:221], v[48:51]
	v_mfma_f32_16x16x32_bf16 v[40:43], v[160:163], v[218:221], v[40:43]
	v_mfma_f32_16x16x32_bf16 v[32:35], v[152:155], v[226:229], v[32:35]
	v_mfma_f32_16x16x32_bf16 v[24:27], v[160:163], v[226:229], v[24:27]
	v_mfma_f32_16x16x32_bf16 v[16:19], v[152:155], v[234:237], v[16:19]
	v_mfma_f32_16x16x32_bf16 v[8:11], v[160:163], v[234:237], v[8:11]
	v_mfma_f32_16x16x32_bf16 v[64:67], v[156:159], v[214:217], v[64:67]
	v_mfma_f32_16x16x32_bf16 v[56:59], v[192:195], v[214:217], v[56:59]
	v_mfma_f32_16x16x32_bf16 v[48:51], v[156:159], v[222:225], v[48:51]
	v_mfma_f32_16x16x32_bf16 v[40:43], v[192:195], v[222:225], v[40:43]
	s_barrier
	v_mfma_f32_16x16x32_bf16 v[32:35], v[156:159], v[230:233], v[32:35]
	v_mfma_f32_16x16x32_bf16 v[24:27], v[192:195], v[230:233], v[24:27]
	v_mfma_f32_16x16x32_bf16 v[16:19], v[156:159], v[238:241], v[16:19]
	v_mfma_f32_16x16x32_bf16 v[8:11], v[192:195], v[238:241], v[8:11]
	s_setprio 0
	s_cmp_gt_u32 s55, 13
	s_cbranch_scc0 .LBB0_257
	s_and_b64 vcc, exec, s[10:11]
	s_cbranch_vccz .LBB0_260
	s_barrier
	s_setprio 1
